# grid-barrier poll loops: back-off lengthened from s_sleep 1 to s_sleep 4, on top of ring peel
# speedup vs baseline: 1.0055x; 1.0005x over previous
; __global__ void __launch_bounds__(NTHREADS) mega_fwd(P p) {
;     ...
;     if (p.ws == nullptr) grid.sync();
.LBB0_36:
	s_sleep 4
	global_load_dword v2, v0, s[2:3] offset:32 sc1
	s_waitcnt vmcnt(0)
	v_and_b32_e32 v2, 0xffff0000, v2
	v_cmp_ne_u32_e32 vcc, v2, v1
	s_or_b64 s[10:11], vcc, s[10:11]
	s_andn2_b64 exec, exec, s[10:11]
	s_cbranch_execnz .LBB0_36

; __device__ __forceinline__ unsigned xb_ld(unsigned* p)              { return __hip_atomic_load(p, __ATOMIC_RELAXED, __HIP_MEMORY_SCOPE_AGENT); }
; __device__ __forceinline__ void xcd_barrier_complete(unsigned* bar, unsigned x, unsigned& nloc, unsigned& nx) {
;     const unsigned G = gridDim.x * gridDim.y * gridDim.z;
;     unsigned sum, cnt, mine, sp = 0u;
;     for (;;) {
;         sum = 0u; cnt = 0u; mine = 0u;
; #pragma unroll
;         for (unsigned j = 0; j < 16; ++j) { const unsigned c = xb_ld(&bar[XB_XCNT(j)]); sum += c; cnt += (c > 0u) ? 1u : 0u; mine = (j == x) ? c : mine; }
;         if (sum == G) break;
;         __builtin_amdgcn_s_sleep(1);
;         if ((++sp & 255u) == 0u) { if (xb_ld(&bar[XB_TMO])) break; if (sp > XB_SPIN_CAP) { atomicAdd(&bar[XB_TMO], 1u); break; } }
;     }
;     nloc = mine > 0u ? mine : 1u; nx = cnt > 0u ? cnt : 1u;
; }
.LBB0_45:
	global_load_dword v15, v16, s[36:37] offset:1024 sc1
	s_waitcnt lgkmcnt(0)
	global_load_dword v0, v16, s[36:37] offset:1280 sc1
	global_load_dword v1, v16, s[36:37] offset:1536 sc1
	global_load_dword v2, v16, s[36:37] offset:1792 sc1
	global_load_dword v3, v16, s[36:37] offset:2048 sc1
	global_load_dword v4, v16, s[36:37] offset:2304 sc1
	global_load_dword v5, v16, s[36:37] offset:2560 sc1
	global_load_dword v6, v16, s[36:37] offset:2816 sc1
	global_load_dword v7, v16, s[36:37] offset:3072 sc1
	global_load_dword v8, v16, s[36:37] offset:3328 sc1
	global_load_dword v9, v16, s[36:37] offset:3584 sc1
	global_load_dword v10, v16, s[36:37] offset:3840 sc1
	global_load_dword v11, v16, s[6:7] sc1
	global_load_dword v12, v16, s[8:9] sc1
	global_load_dword v13, v16, s[10:11] sc1
	global_load_dword v14, v16, s[12:13] sc1
	s_mov_b64 s[14:15], -1
	s_mov_b64 s[16:17], -1
	s_waitcnt vmcnt(14)
	v_add_u32_e32 v17, v0, v15
	s_waitcnt vmcnt(13)
	v_add_u32_e32 v17, v17, v1
	s_waitcnt vmcnt(12)
	v_add_u32_e32 v17, v17, v2
	s_waitcnt vmcnt(11)
	v_add_u32_e32 v17, v17, v3
	s_waitcnt vmcnt(10)
	v_add_u32_e32 v17, v17, v4
	s_waitcnt vmcnt(9)
	v_add_u32_e32 v17, v17, v5
	s_waitcnt vmcnt(8)
	v_add_u32_e32 v17, v17, v6
	s_waitcnt vmcnt(7)
	v_add_u32_e32 v17, v17, v7
	s_waitcnt vmcnt(6)
	v_add_u32_e32 v17, v17, v8
	s_waitcnt vmcnt(5)
	v_add_u32_e32 v17, v17, v9
	s_waitcnt vmcnt(4)
	v_add_u32_e32 v17, v17, v10
	s_waitcnt vmcnt(3)
	v_add_u32_e32 v17, v17, v11
	s_waitcnt vmcnt(2)
	v_add_u32_e32 v17, v17, v12
	s_waitcnt vmcnt(1)
	v_add_u32_e32 v17, v17, v13
	s_waitcnt vmcnt(0)
	v_add_u32_e32 v17, v17, v14
	v_cmp_eq_u32_e32 vcc, s5, v17
	s_cbranch_vccnz .LBB0_44
	s_and_b32 s14, s20, 0xff
	s_cmp_eq_u32 s14, 0
	s_mov_b64 s[14:15], -1
	s_mov_b64 s[18:19], -1
	s_sleep 4
	s_cbranch_scc1 .LBB0_49
	s_and_b64 vcc, exec, s[18:19]
	s_cbranch_vccz .LBB0_44

; __device__ __forceinline__ unsigned xb_ld(unsigned* p)              { return __hip_atomic_load(p, __ATOMIC_RELAXED, __HIP_MEMORY_SCOPE_AGENT); }
; __device__ __forceinline__ unsigned xb_add(unsigned* p, unsigned v) { return __hip_atomic_fetch_add(p, v, __ATOMIC_RELAXED, __HIP_MEMORY_SCOPE_AGENT); }
; #define XB_SPIN(cond, bar) do { unsigned _sp = 0; while (cond) { __builtin_amdgcn_s_sleep(1); \
;     if ((++_sp & 255u) == 0u) { if (xb_ld(&(bar)[XB_TMO])) break; if (_sp > XB_SPIN_CAP) { atomicAdd(&(bar)[XB_TMO], 1u); break; } } } } while (0)
; __device__ __forceinline__ void xcd_barrier(const XcdBarrier& b) {
;     ...
;             else XB_SPIN(xb_ld(&bar[XB_TOPGEN]) == tg, bar);
;             __builtin_amdgcn_fence(__ATOMIC_ACQUIRE, "agent");
;             xb_add(&bar[XB_XGEN(b.x)], 1u);
;             asm volatile("s_waitcnt vmcnt(0)" ::: "memory");
;         } else {
;             XB_SPIN(xb_ld(&bar[XB_XGEN(b.x)]) == gen, bar);
.LBB0_63:
	s_and_b32 s22, s5, 0xff
	s_mov_b64 s[20:21], -1
	s_cmp_lg_u32 s22, 0
	s_mov_b64 s[24:25], -1
	s_sleep 4
	s_cbranch_scc0 .LBB0_66
	s_and_b64 vcc, exec, s[24:25]
	s_cbranch_vccz .LBB0_62

; __device__ __forceinline__ unsigned xb_ld(unsigned* p)              { return __hip_atomic_load(p, __ATOMIC_RELAXED, __HIP_MEMORY_SCOPE_AGENT); }
; __device__ __forceinline__ unsigned xb_add(unsigned* p, unsigned v) { return __hip_atomic_fetch_add(p, v, __ATOMIC_RELAXED, __HIP_MEMORY_SCOPE_AGENT); }
; #define XB_SPIN(cond, bar) do { unsigned _sp = 0; while (cond) { __builtin_amdgcn_s_sleep(1); \
;     if ((++_sp & 255u) == 0u) { if (xb_ld(&(bar)[XB_TMO])) break; if (_sp > XB_SPIN_CAP) { atomicAdd(&(bar)[XB_TMO], 1u); break; } } } } while (0)
; __device__ __forceinline__ void xcd_barrier(const XcdBarrier& b) {
;     ...
;             else XB_SPIN(xb_ld(&bar[XB_TOPGEN]) == tg, bar);
;             __builtin_amdgcn_fence(__ATOMIC_ACQUIRE, "agent");
;             xb_add(&bar[XB_XGEN(b.x)], 1u);
;             asm volatile("s_waitcnt vmcnt(0)" ::: "memory");
;         } else {
;             XB_SPIN(xb_ld(&bar[XB_XGEN(b.x)]) == gen, bar);
.LBB0_80:
	s_and_b32 s24, s5, 0xff
	s_cmp_lg_u32 s24, 0
	s_mov_b64 s[26:27], -1
	s_sleep 4
	s_cbranch_scc0 .LBB0_83
	s_mov_b64 s[28:29], -1
	s_and_b64 vcc, exec, s[26:27]
	s_cbranch_vccz .LBB0_79

; __device__ __forceinline__ unsigned xb_ld(unsigned* p)              { return __hip_atomic_load(p, __ATOMIC_RELAXED, __HIP_MEMORY_SCOPE_AGENT); }
; __device__ __forceinline__ void xcd_barrier_complete(unsigned* bar, unsigned x, unsigned& nloc, unsigned& nx) {
;     const unsigned G = gridDim.x * gridDim.y * gridDim.z;
;     unsigned sum, cnt, mine, sp = 0u;
;     for (;;) {
;         sum = 0u; cnt = 0u; mine = 0u;
; #pragma unroll
;         for (unsigned j = 0; j < 16; ++j) { const unsigned c = xb_ld(&bar[XB_XCNT(j)]); sum += c; cnt += (c > 0u) ? 1u : 0u; mine = (j == x) ? c : mine; }
;         if (sum == G) break;
;         __builtin_amdgcn_s_sleep(1);
;         if ((++sp & 255u) == 0u) { if (xb_ld(&bar[XB_TMO])) break; if (sp > XB_SPIN_CAP) { atomicAdd(&bar[XB_TMO], 1u); break; } }
;     }
;     nloc = mine > 0u ? mine : 1u; nx = cnt > 0u ? cnt : 1u;
; }
.LBB0_108:
	v_readlane_b32 s6, v253, 11
	v_readlane_b32 s7, v253, 12
	global_load_dword v12, v1, s[36:37] offset:1024 sc1
	global_load_dword v0, v1, s[36:37] offset:1280 sc1
	s_waitcnt lgkmcnt(0)
	global_load_dword v2, v1, s[36:37] offset:1536 sc1
	global_load_dword v3, v1, s[36:37] offset:1792 sc1
	global_load_dword v4, v1, s[36:37] offset:2048 sc1
	global_load_dword v5, v1, s[36:37] offset:2304 sc1
	global_load_dword v6, v1, s[36:37] offset:2560 sc1
	global_load_dword v7, v1, s[36:37] offset:2816 sc1
	global_load_dword v8, v1, s[36:37] offset:3072 sc1
	global_load_dword v9, v1, s[36:37] offset:3328 sc1
	global_load_dword v10, v1, s[36:37] offset:3584 sc1
	global_load_dword v11, v1, s[36:37] offset:3840 sc1
	global_load_dword v13, v1, s[6:7] sc1
	v_readlane_b32 s6, v253, 13
	v_readlane_b32 s7, v253, 14
	v_readlane_b32 s8, v253, 8
	s_waitcnt vmcnt(11)
	v_add_u32_e32 v17, v0, v12
	s_nop 1
	global_load_dword v14, v1, s[6:7] sc1
	v_readlane_b32 s6, v253, 15
	v_readlane_b32 s7, v253, 16
	s_waitcnt vmcnt(11)
	v_add_u32_e32 v17, v17, v2
	s_waitcnt vmcnt(10)
	v_add_u32_e32 v17, v17, v3
	s_waitcnt vmcnt(9)
	v_add_u32_e32 v17, v17, v4
	s_waitcnt vmcnt(8)
	v_add_u32_e32 v17, v17, v5
	s_waitcnt vmcnt(7)
	v_add_u32_e32 v17, v17, v6
	global_load_dword v15, v1, s[6:7] sc1
	v_readlane_b32 s6, v253, 17
	v_readlane_b32 s7, v253, 18
	s_waitcnt vmcnt(7)
	v_add_u32_e32 v17, v17, v7
	s_waitcnt vmcnt(6)
	v_add_u32_e32 v17, v17, v8
	s_waitcnt vmcnt(5)
	v_add_u32_e32 v17, v17, v9
	s_waitcnt vmcnt(4)
	v_add_u32_e32 v17, v17, v10
	s_waitcnt vmcnt(3)
	v_add_u32_e32 v17, v17, v11
	global_load_dword v16, v1, s[6:7] sc1
	s_waitcnt vmcnt(3)
	v_add_u32_e32 v17, v17, v13
	s_mov_b64 s[6:7], -1
	s_waitcnt vmcnt(2)
	v_add_u32_e32 v17, v17, v14
	s_waitcnt vmcnt(1)
	v_add_u32_e32 v17, v17, v15
	s_waitcnt vmcnt(0)
	v_add_u32_e32 v17, v17, v16
	v_cmp_eq_u32_e32 vcc, s8, v17
	s_mov_b64 s[8:9], -1
	s_cbranch_vccnz .LBB0_107
	s_and_b32 s6, s12, 0xff
	s_cmp_eq_u32 s6, 0
	s_mov_b64 s[6:7], -1
	s_mov_b64 s[10:11], -1
	s_sleep 4
	s_cbranch_scc1 .LBB0_112
	s_and_b64 vcc, exec, s[10:11]
	s_cbranch_vccz .LBB0_107

; __device__ __forceinline__ unsigned xb_ld(unsigned* p)              { return __hip_atomic_load(p, __ATOMIC_RELAXED, __HIP_MEMORY_SCOPE_AGENT); }
; __device__ __forceinline__ unsigned xb_add(unsigned* p, unsigned v) { return __hip_atomic_fetch_add(p, v, __ATOMIC_RELAXED, __HIP_MEMORY_SCOPE_AGENT); }
; #define XB_SPIN(cond, bar) do { unsigned _sp = 0; while (cond) { __builtin_amdgcn_s_sleep(1); \
;     if ((++_sp & 255u) == 0u) { if (xb_ld(&(bar)[XB_TMO])) break; if (_sp > XB_SPIN_CAP) { atomicAdd(&(bar)[XB_TMO], 1u); break; } } } } while (0)
; __device__ __forceinline__ void xcd_barrier(const XcdBarrier& b) {
;     ...
;             else XB_SPIN(xb_ld(&bar[XB_TOPGEN]) == tg, bar);
;             __builtin_amdgcn_fence(__ATOMIC_ACQUIRE, "agent");
;             xb_add(&bar[XB_XGEN(b.x)], 1u);
;             asm volatile("s_waitcnt vmcnt(0)" ::: "memory");
;         } else {
;             XB_SPIN(xb_ld(&bar[XB_XGEN(b.x)]) == gen, bar);
.LBB0_124:
	s_and_b32 s16, s20, 0xff
	s_mov_b64 s[14:15], -1
	s_cmp_lg_u32 s16, 0
	s_mov_b64 s[18:19], -1
	s_sleep 4
	s_cbranch_scc0 .LBB0_127
	s_and_b64 vcc, exec, s[18:19]
	s_cbranch_vccz .LBB0_123

; __device__ __forceinline__ unsigned xb_ld(unsigned* p)              { return __hip_atomic_load(p, __ATOMIC_RELAXED, __HIP_MEMORY_SCOPE_AGENT); }
; __device__ __forceinline__ unsigned xb_add(unsigned* p, unsigned v) { return __hip_atomic_fetch_add(p, v, __ATOMIC_RELAXED, __HIP_MEMORY_SCOPE_AGENT); }
; #define XB_SPIN(cond, bar) do { unsigned _sp = 0; while (cond) { __builtin_amdgcn_s_sleep(1); \
;     if ((++_sp & 255u) == 0u) { if (xb_ld(&(bar)[XB_TMO])) break; if (_sp > XB_SPIN_CAP) { atomicAdd(&(bar)[XB_TMO], 1u); break; } } } } while (0)
; __device__ __forceinline__ void xcd_barrier(const XcdBarrier& b) {
;     ...
;             else XB_SPIN(xb_ld(&bar[XB_TOPGEN]) == tg, bar);
;             __builtin_amdgcn_fence(__ATOMIC_ACQUIRE, "agent");
;             xb_add(&bar[XB_XGEN(b.x)], 1u);
;             asm volatile("s_waitcnt vmcnt(0)" ::: "memory");
;         } else {
;             XB_SPIN(xb_ld(&bar[XB_XGEN(b.x)]) == gen, bar);
.LBB0_141:
	s_and_b32 s18, s22, 0xff
	s_mov_b64 s[16:17], -1
	s_cmp_lg_u32 s18, 0
	s_mov_b64 s[20:21], -1
	s_sleep 4
	s_cbranch_scc0 .LBB0_144
	s_and_b64 vcc, exec, s[20:21]
	s_cbranch_vccz .LBB0_140

; __device__ __forceinline__ unsigned xb_ld(unsigned* p)              { return __hip_atomic_load(p, __ATOMIC_RELAXED, __HIP_MEMORY_SCOPE_AGENT); }
; __device__ __forceinline__ void xcd_barrier_complete(unsigned* bar, unsigned x, unsigned& nloc, unsigned& nx) {
;     const unsigned G = gridDim.x * gridDim.y * gridDim.z;
;     unsigned sum, cnt, mine, sp = 0u;
;     for (;;) {
;         sum = 0u; cnt = 0u; mine = 0u;
; #pragma unroll
;         for (unsigned j = 0; j < 16; ++j) { const unsigned c = xb_ld(&bar[XB_XCNT(j)]); sum += c; cnt += (c > 0u) ? 1u : 0u; mine = (j == x) ? c : mine; }
;         if (sum == G) break;
;         __builtin_amdgcn_s_sleep(1);
;         if ((++sp & 255u) == 0u) { if (xb_ld(&bar[XB_TMO])) break; if (sp > XB_SPIN_CAP) { atomicAdd(&bar[XB_TMO], 1u); break; } }
;     }
;     nloc = mine > 0u ? mine : 1u; nx = cnt > 0u ? cnt : 1u;
; }
.LBB0_792:
	v_readlane_b32 s12, v253, 11
	v_readlane_b32 s13, v253, 12
	global_load_dword v12, v1, s[36:37] offset:1024 sc1
	global_load_dword v0, v1, s[36:37] offset:1280 sc1
	s_waitcnt lgkmcnt(0)
	global_load_dword v2, v1, s[36:37] offset:1536 sc1
	global_load_dword v3, v1, s[36:37] offset:1792 sc1
	global_load_dword v4, v1, s[36:37] offset:2048 sc1
	global_load_dword v5, v1, s[36:37] offset:2304 sc1
	global_load_dword v6, v1, s[36:37] offset:2560 sc1
	global_load_dword v7, v1, s[36:37] offset:2816 sc1
	global_load_dword v8, v1, s[36:37] offset:3072 sc1
	global_load_dword v9, v1, s[36:37] offset:3328 sc1
	global_load_dword v10, v1, s[36:37] offset:3584 sc1
	global_load_dword v11, v1, s[36:37] offset:3840 sc1
	global_load_dword v13, v1, s[12:13] sc1
	v_readlane_b32 s12, v253, 13
	v_readlane_b32 s13, v253, 14
	v_readlane_b32 s14, v253, 8
	s_waitcnt vmcnt(11)
	v_add_u32_e32 v17, v0, v12
	s_nop 1
	global_load_dword v14, v1, s[12:13] sc1
	v_readlane_b32 s12, v253, 15
	v_readlane_b32 s13, v253, 16
	s_waitcnt vmcnt(11)
	v_add_u32_e32 v17, v17, v2
	s_waitcnt vmcnt(10)
	v_add_u32_e32 v17, v17, v3
	s_waitcnt vmcnt(9)
	v_add_u32_e32 v17, v17, v4
	s_waitcnt vmcnt(8)
	v_add_u32_e32 v17, v17, v5
	s_waitcnt vmcnt(7)
	v_add_u32_e32 v17, v17, v6
	global_load_dword v15, v1, s[12:13] sc1
	v_readlane_b32 s12, v253, 17
	v_readlane_b32 s13, v253, 18
	s_waitcnt vmcnt(7)
	v_add_u32_e32 v17, v17, v7
	s_waitcnt vmcnt(6)
	v_add_u32_e32 v17, v17, v8
	s_waitcnt vmcnt(5)
	v_add_u32_e32 v17, v17, v9
	s_waitcnt vmcnt(4)
	v_add_u32_e32 v17, v17, v10
	s_waitcnt vmcnt(3)
	v_add_u32_e32 v17, v17, v11
	global_load_dword v16, v1, s[12:13] sc1
	s_waitcnt vmcnt(3)
	v_add_u32_e32 v17, v17, v13
	s_mov_b64 s[12:13], -1
	s_waitcnt vmcnt(2)
	v_add_u32_e32 v17, v17, v14
	s_waitcnt vmcnt(1)
	v_add_u32_e32 v17, v17, v15
	s_waitcnt vmcnt(0)
	v_add_u32_e32 v17, v17, v16
	v_cmp_eq_u32_e32 vcc, s14, v17
	s_mov_b64 s[14:15], -1
	s_cbranch_vccnz .LBB0_791
	s_and_b32 s12, s18, 0xff
	s_cmp_eq_u32 s12, 0
	s_mov_b64 s[12:13], -1
	s_mov_b64 s[16:17], -1
	s_sleep 4
	s_cbranch_scc1 .LBB0_796
	s_and_b64 vcc, exec, s[16:17]
	s_cbranch_vccz .LBB0_791

; __device__ __forceinline__ unsigned xb_ld(unsigned* p)              { return __hip_atomic_load(p, __ATOMIC_RELAXED, __HIP_MEMORY_SCOPE_AGENT); }
; __device__ __forceinline__ unsigned xb_add(unsigned* p, unsigned v) { return __hip_atomic_fetch_add(p, v, __ATOMIC_RELAXED, __HIP_MEMORY_SCOPE_AGENT); }
; #define XB_SPIN(cond, bar) do { unsigned _sp = 0; while (cond) { __builtin_amdgcn_s_sleep(1); \
;     if ((++_sp & 255u) == 0u) { if (xb_ld(&(bar)[XB_TMO])) break; if (_sp > XB_SPIN_CAP) { atomicAdd(&(bar)[XB_TMO], 1u); break; } } } } while (0)
; __device__ __forceinline__ void xcd_barrier(const XcdBarrier& b) {
;     ...
;             else XB_SPIN(xb_ld(&bar[XB_TOPGEN]) == tg, bar);
;             __builtin_amdgcn_fence(__ATOMIC_ACQUIRE, "agent");
;             xb_add(&bar[XB_XGEN(b.x)], 1u);
;             asm volatile("s_waitcnt vmcnt(0)" ::: "memory");
;         } else {
;             XB_SPIN(xb_ld(&bar[XB_XGEN(b.x)]) == gen, bar);
.LBB0_808:
	s_and_b32 s22, s26, 0xff
	s_mov_b64 s[20:21], -1
	s_cmp_lg_u32 s22, 0
	s_mov_b64 s[24:25], -1
	s_sleep 4
	s_cbranch_scc0 .LBB0_811
	s_and_b64 vcc, exec, s[24:25]
	s_cbranch_vccz .LBB0_807
